# row-prep phases: non-temporal (streaming) hint on the x / m row loads so the read-once residual stream does not evict h, weights and activations from L2 / Infinity Cache
# speedup vs baseline: 1.0263x; 1.0263x over previous
; __device__ __forceinline__ int otid() { int t = threadIdx.x; asm volatile("" : "+v"(t)); return t; }
; __device__ __forceinline__ int obid() { int t = blockIdx.x; asm volatile("" : "+s"(t)); return t; }
; __device__ void phase_rowprep(const float* xsrc, const bf16_t* __restrict__ m, const float* __restrict__ gpost, float* xdst, const float* __restrict__ gpre, bf16_t* __restrict__ hdst) {
;     const int tid = otid(); const int lane = tid & 63, wave = tid >> 6;
;     const int stride = gridDim.x * 8;
;     f32x4 gp[4], gq[4];
; #pragma unroll
;     for (int i = 0; i < 4; ++i) { gp[i] = m ? *(const f32x4*)(gpost + i * 256 + lane * 4) : (f32x4){0.f, 0.f, 0.f, 0.f}; gq[i] = hdst ? *(const f32x4*)(gpre + i * 256 + lane * 4) : (f32x4){0.f, 0.f, 0.f, 0.f}; }
;     int row = obid() * 8 + wave;
;     f32x4 xn[4]; bf16x4 mn[4];
;     if (row < S) {
; #pragma unroll
;         for (int i = 0; i < 4; ++i) { xn[i] = *(const f32x4*)(xsrc + (size_t)row * D + i * 256 + lane * 4); mn[i] = m ? *(const bf16x4*)(m + (size_t)row * D + i * 256 + lane * 4) : (bf16x4){0, 0, 0, 0}; }
;     }
;     while (row < S) {
;         f32x4 xv[4]; bf16x4 mb[4];
; #pragma unroll
;         for (int i = 0; i < 4; ++i) { xv[i] = xn[i]; mb[i] = mn[i]; }
;         const int nrow = row + stride;
;         if (nrow < S) {
; #pragma unroll
;             for (int i = 0; i < 4; ++i) { xn[i] = *(const f32x4*)(xsrc + (size_t)nrow * D + i * 256 + lane * 4); mn[i] = m ? *(const bf16x4*)(m + (size_t)nrow * D + i * 256 + lane * 4) : (bf16x4){0, 0, 0, 0}; }
;         }
.LBB0_121:
	v_mov_b32_e32 v48, v245
	s_mov_b32 s0, s2
	v_ashrrev_i32_e32 v0, 6, v48
	s_nop 0
	v_lshl_add_u32 v64, s0, 3, v0
	v_cmp_gt_i32_e32 vcc, s80, v64
	s_and_saveexec_b64 s[4:5], vcc
	s_cbranch_execz .LBB0_128
	v_readlane_b32 s0, v255, 16
	v_readlane_b32 s1, v255, 17
	s_mov_b32 s6, s0
	s_ashr_i32 s7, s0, 31
	v_writelane_b32 v255, s0, 16
	v_readlane_b32 s64, v254, 27
	v_readlane_b32 s68, v254, 31
	v_writelane_b32 v255, s1, 17
	s_lshl_b64 s[0:1], s[6:7], 12
	v_readlane_b32 s69, v254, 32
	s_add_u32 s6, s68, s0
	s_addc_u32 s7, s69, s1
	v_readlane_b32 s8, v253, 0
	s_add_u32 s0, s8, s0
	s_load_dword s8, s[52:53], 0x0
	v_lshlrev_b32_e32 v0, 2, v48
	v_and_b32_e32 v36, 0xfc, v0
	v_readlane_b32 s9, v253, 1
	v_lshlrev_b32_e32 v176, 2, v36
	s_addc_u32 s1, s9, s1
	global_load_dwordx4 v[0:3], v176, s[6:7]
	global_load_dwordx4 v[4:7], v176, s[0:1]
	global_load_dwordx4 v[8:11], v176, s[6:7] offset:1024
	global_load_dwordx4 v[12:15], v176, s[0:1] offset:1024
	global_load_dwordx4 v[16:19], v176, s[6:7] offset:2048
	global_load_dwordx4 v[20:23], v176, s[0:1] offset:2048
	global_load_dwordx4 v[24:27], v176, s[6:7] offset:3072
	global_load_dwordx4 v[28:31], v176, s[0:1] offset:3072
	s_waitcnt lgkmcnt(0)
	s_lshl_b32 s6, s8, 3
	s_add_i32 s0, s85, 8
	v_readlane_b32 s65, v254, 28
	s_cmp_lt_u32 s0, 17
	v_ashrrev_i32_e32 v65, 31, v64
	s_cselect_b32 s1, s65, s59
	s_cselect_b32 s0, s64, s58
	v_lshlrev_b64 v[50:51], 12, v[64:65]
	v_readlane_b32 s8, v253, 18
	v_lshl_add_u64 v[32:33], s[0:1], 0, v[50:51]
	v_lshlrev_b64 v[52:53], 11, v[64:65]
	v_readlane_b32 s9, v253, 19
	v_lshl_add_u64 v[32:33], v[32:33], 0, v[176:177]
	v_lshlrev_b32_e32 v176, 1, v36
	v_lshl_add_u64 v[34:35], s[8:9], 0, v[52:53]
	v_lshl_add_u64 v[54:55], v[34:35], 0, v[176:177]
	global_load_dwordx4 v[44:47], v[32:33], off nt
	global_load_dwordx2 v[90:91], v[54:55], off nt
	global_load_dwordx4 v[40:43], v[32:33], off offset:1024 nt
	global_load_dwordx2 v[88:89], v[54:55], off offset:512 nt
	global_load_dwordx4 v[36:39], v[32:33], off offset:2048 nt
	global_load_dwordx2 v[86:87], v[54:55], off offset:1024 nt
	s_nop 0
	global_load_dwordx4 v[32:35], v[32:33], off offset:3072 nt
	s_nop 0
	global_load_dwordx2 v[84:85], v[54:55], off offset:1536 nt
	v_and_b32_e32 v49, 64, v228
	v_add_u32_e32 v49, 64, v49
	v_xor_b32_e32 v54, 32, v228
	v_cmp_lt_i32_e32 vcc, v54, v49
	v_and_b32_e32 v48, 63, v48
	v_lshlrev_b32_e32 v176, 3, v48
	v_cndmask_b32_e32 v54, v228, v54, vcc
	v_lshlrev_b32_e32 v65, 2, v54
	v_xor_b32_e32 v54, 16, v228
	v_cmp_lt_i32_e32 vcc, v54, v49
	v_lshlrev_b32_e32 v68, 4, v48
	v_add_u32_e32 v48, s6, v64
	v_cndmask_b32_e32 v54, v228, v54, vcc
	v_lshlrev_b32_e32 v92, 2, v54
	v_xor_b32_e32 v54, 8, v228
	v_cmp_lt_i32_e32 vcc, v54, v49
	v_lshl_add_u64 v[70:71], s[58:59], 0, v[50:51]
	v_readlane_b32 s10, v253, 2
	v_cndmask_b32_e32 v54, v228, v54, vcc
	v_lshlrev_b32_e32 v93, 2, v54
	v_xor_b32_e32 v54, 4, v228
	v_cmp_lt_i32_e32 vcc, v54, v49
	v_readlane_b32 s11, v253, 3
	v_readlane_b32 s12, v253, 4
	v_cndmask_b32_e32 v54, v228, v54, vcc
	v_lshlrev_b32_e32 v94, 2, v54
	v_xor_b32_e32 v54, 2, v228
	v_cmp_lt_i32_e32 vcc, v54, v49
	v_readlane_b32 s13, v253, 5
	v_lshl_add_u64 v[66:67], s[60:61], 0, v[52:53]
	v_cndmask_b32_e32 v54, v228, v54, vcc
	v_lshlrev_b32_e32 v95, 2, v54
	v_xor_b32_e32 v54, 1, v228
	v_cmp_lt_i32_e32 vcc, v54, v49
	s_ashr_i32 s7, s6, 31
	s_lshl_b64 s[8:9], s[6:7], 11
	v_cndmask_b32_e32 v49, v228, v54, vcc
	v_lshlrev_b32_e32 v96, 2, v49
	v_ashrrev_i32_e32 v49, 31, v48
	v_lshlrev_b64 v[50:51], 12, v[48:49]
	v_lshlrev_b64 v[48:49], 11, v[48:49]
	v_lshl_add_u64 v[72:73], s[0:1], 0, v[50:51]
	v_lshl_add_u64 v[74:75], s[60:61], 0, v[48:49]
	v_mov_b32_e32 v69, v177
	s_lshl_b64 s[10:11], s[6:7], 12
	s_mov_b64 s[12:13], 0
	v_readlane_b32 s66, v254, 29
	v_readlane_b32 s67, v254, 30
	v_readlane_b32 s70, v254, 33
	v_readlane_b32 s71, v254, 34
	v_readlane_b32 s72, v254, 35
	v_readlane_b32 s73, v254, 36
	v_readlane_b32 s74, v254, 37
	v_readlane_b32 s75, v254, 38
	v_readlane_b32 s76, v254, 39
	v_readlane_b32 s77, v254, 40
	v_readlane_b32 s78, v254, 41
	v_readlane_b32 s79, v254, 42
	v_readlane_b32 s14, v253, 6
	v_readlane_b32 s15, v253, 7
	s_waitcnt vmcnt(7)
	v_mov_b64_e32 v[50:51], v[46:47]
	s_waitcnt vmcnt(6)
	v_mov_b64_e32 v[76:77], v[90:91]
	s_waitcnt vmcnt(5)
	v_mov_b64_e32 v[54:55], v[42:43]
	s_waitcnt vmcnt(4)
	v_mov_b64_e32 v[78:79], v[88:89]
	s_waitcnt vmcnt(3)
	v_mov_b64_e32 v[58:59], v[38:39]
	s_waitcnt vmcnt(2)
	v_mov_b64_e32 v[80:81], v[86:87]
	s_waitcnt vmcnt(1)
	v_mov_b64_e32 v[62:63], v[34:35]
	s_waitcnt vmcnt(0)
	v_mov_b64_e32 v[82:83], v[84:85]
	v_mov_b64_e32 v[48:49], v[44:45]
	v_mov_b64_e32 v[52:53], v[40:41]
	v_mov_b64_e32 v[56:57], v[36:37]
	v_mov_b64_e32 v[60:61], v[32:33]
	s_branch .LBB0_124

; __device__ void phase_rowprep(const float* xsrc, const bf16_t* __restrict__ m, const float* __restrict__ gpost, float* xdst, const float* __restrict__ gpre, bf16_t* __restrict__ hdst) {
;     ...
;         const int nrow = row + stride;
;         if (nrow < S) {
; #pragma unroll
;             for (int i = 0; i < 4; ++i) { xn[i] = *(const f32x4*)(xsrc + (size_t)nrow * D + i * 256 + lane * 4); mn[i] = m ? *(const bf16x4*)(m + (size_t)nrow * D + i * 256 + lane * 4) : (bf16x4){0, 0, 0, 0}; }
;         }
.LBB0_124:
	v_add_u32_e32 v64, s6, v64
	v_cmp_gt_i32_e32 vcc, s80, v64
	v_cmp_lt_i32_e64 s[0:1], s82, v64
	s_and_saveexec_b64 s[14:15], vcc
	s_cbranch_execz .LBB0_126
	v_lshl_add_u64 v[48:49], v[74:75], 0, v[176:177]
	v_add_co_u32_e32 v82, vcc, 0x9058000, v48
	v_lshl_add_u64 v[60:61], v[72:73], 0, v[68:69]
	s_nop 0
	v_addc_co_u32_e32 v83, vcc, 0, v49, vcc
	global_load_dwordx4 v[48:51], v[60:61], off nt
	global_load_dwordx4 v[52:55], v[60:61], off offset:1024 nt
	global_load_dwordx4 v[56:59], v[60:61], off offset:2048 nt
	s_nop 0
	global_load_dwordx4 v[60:63], v[60:61], off offset:3072 nt
	s_nop 0
	global_load_dwordx2 v[76:77], v[82:83], off nt
	global_load_dwordx2 v[78:79], v[82:83], off offset:512 nt
	global_load_dwordx2 v[80:81], v[82:83], off offset:1024 nt
	s_nop 0
	global_load_dwordx2 v[82:83], v[82:83], off offset:1536 nt

; __device__ __forceinline__ int otid() { int t = threadIdx.x; asm volatile("" : "+v"(t)); return t; }
; __device__ __forceinline__ int obid() { int t = blockIdx.x; asm volatile("" : "+s"(t)); return t; }
; __device__ void phase_rowprep(const float* xsrc, const bf16_t* __restrict__ m, const float* __restrict__ gpost, float* xdst, const float* __restrict__ gpre, bf16_t* __restrict__ hdst) {
;     const int tid = otid(); const int lane = tid & 63, wave = tid >> 6;
;     const int stride = gridDim.x * 8;
;     f32x4 gp[4], gq[4];
; #pragma unroll
;     for (int i = 0; i < 4; ++i) { gp[i] = m ? *(const f32x4*)(gpost + i * 256 + lane * 4) : (f32x4){0.f, 0.f, 0.f, 0.f}; gq[i] = hdst ? *(const f32x4*)(gpre + i * 256 + lane * 4) : (f32x4){0.f, 0.f, 0.f, 0.f}; }
;     int row = obid() * 8 + wave;
;     f32x4 xn[4]; bf16x4 mn[4];
;     if (row < S) {
; #pragma unroll
;         for (int i = 0; i < 4; ++i) { xn[i] = *(const f32x4*)(xsrc + (size_t)row * D + i * 256 + lane * 4); mn[i] = m ? *(const bf16x4*)(m + (size_t)row * D + i * 256 + lane * 4) : (bf16x4){0, 0, 0, 0}; }
;     }
;     while (row < S) {
;         f32x4 xv[4]; bf16x4 mb[4];
; #pragma unroll
;         for (int i = 0; i < 4; ++i) { xv[i] = xn[i]; mb[i] = mn[i]; }
;         const int nrow = row + stride;
;         if (nrow < S) {
; #pragma unroll
;             for (int i = 0; i < 4; ++i) { xn[i] = *(const f32x4*)(xsrc + (size_t)nrow * D + i * 256 + lane * 4); mn[i] = m ? *(const bf16x4*)(m + (size_t)nrow * D + i * 256 + lane * 4) : (bf16x4){0, 0, 0, 0}; }
;         }
.LBB0_370:
	v_mov_b32_e32 v32, v245
	s_mov_b32 s0, s2
	v_ashrrev_i32_e32 v0, 6, v32
	s_nop 0
	v_lshl_add_u32 v48, s0, 3, v0
	v_cmp_gt_i32_e32 vcc, s80, v48
	s_and_saveexec_b64 s[4:5], vcc
	s_cbranch_execz .LBB0_7
	v_lshlrev_b32_e32 v0, 2, v32
	v_ashrrev_i32_e32 v49, 31, v48
	v_and_b32_e32 v18, 0xfc, v0
	v_readlane_b32 s0, v254, 19
	v_lshlrev_b64 v[16:17], 12, v[48:49]
	v_readlane_b32 s14, v253, 18
	v_lshlrev_b32_e32 v176, 2, v18
	v_readlane_b32 s1, v254, 20
	v_lshl_add_u64 v[50:51], s[58:59], 0, v[16:17]
	v_lshlrev_b64 v[16:17], 11, v[48:49]
	v_readlane_b32 s15, v253, 19
	s_nop 1
	global_load_dwordx4 v[0:3], v176, s[0:1]
	global_load_dwordx4 v[4:7], v176, s[0:1] offset:1024
	global_load_dwordx4 v[8:11], v176, s[0:1] offset:2048
	global_load_dwordx4 v[12:15], v176, s[0:1] offset:3072
	v_lshl_add_u64 v[24:25], v[50:51], 0, v[176:177]
	v_lshl_add_u64 v[16:17], s[14:15], 0, v[16:17]
	v_lshlrev_b32_e32 v176, 1, v18
	v_lshl_add_u64 v[26:27], v[16:17], 0, v[176:177]
	global_load_dwordx4 v[20:23], v[24:25], off nt
	global_load_dwordx4 v[28:31], v[24:25], off offset:1024 nt
	global_load_dwordx4 v[16:19], v[24:25], off offset:2048 nt
	global_load_dwordx2 v[70:71], v[26:27], off nt
	global_load_dwordx2 v[68:69], v[26:27], off offset:512 nt
	global_load_dwordx2 v[60:61], v[26:27], off offset:1024 nt
	global_load_dwordx2 v[56:57], v[26:27], off offset:1536 nt
	s_nop 0
	global_load_dwordx4 v[24:27], v[24:25], off offset:3072 nt
	v_and_b32_e32 v33, 64, v228
	v_xor_b32_e32 v34, 32, v228
	v_and_b32_e32 v40, 63, v32
	v_add_u32_e32 v32, 64, v33
	v_xor_b32_e32 v35, 16, v228
	v_cmp_lt_i32_e32 vcc, v34, v32
	s_load_dword s0, s[52:53], 0x0
	v_xor_b32_e32 v36, 8, v228
	v_cndmask_b32_e32 v33, v228, v34, vcc
	v_cmp_lt_i32_e32 vcc, v35, v32
	v_xor_b32_e32 v37, 4, v228
	v_xor_b32_e32 v38, 2, v228
	v_cndmask_b32_e32 v34, v228, v35, vcc
	v_cmp_lt_i32_e32 vcc, v36, v32
	v_xor_b32_e32 v39, 1, v228
	s_waitcnt lgkmcnt(0)
	s_lshl_b32 s8, s0, 3
	v_cndmask_b32_e32 v35, v228, v36, vcc
	v_cmp_lt_i32_e32 vcc, v37, v32
	v_lshlrev_b32_e32 v49, 2, v33
	v_lshlrev_b32_e32 v82, 2, v34
	v_cndmask_b32_e32 v36, v228, v37, vcc
	v_cmp_lt_i32_e32 vcc, v38, v32
	v_lshlrev_b32_e32 v83, 2, v35
	v_lshlrev_b32_e32 v84, 2, v36
	v_cndmask_b32_e32 v37, v228, v38, vcc
	v_cmp_lt_i32_e32 vcc, v39, v32
	v_lshlrev_b32_e32 v85, 2, v37
	v_lshlrev_b32_e32 v176, 4, v40
	v_cndmask_b32_e32 v32, v228, v39, vcc
	v_lshlrev_b32_e32 v86, 2, v32
	v_add_u32_e32 v32, s8, v48
	v_ashrrev_i32_e32 v33, 31, v32
	v_lshlrev_b64 v[34:35], 12, v[32:33]
	v_lshlrev_b64 v[32:33], 11, v[32:33]
	v_lshl_or_b32 v32, v40, 3, v32
	s_ashr_i32 s9, s8, 31
	v_lshl_add_u64 v[52:53], s[58:59], 0, v[34:35]
	v_lshl_add_u64 v[54:55], s[14:15], 0, v[32:33]
	s_mov_b64 s[6:7], 0
	s_lshl_b64 s[10:11], s[8:9], 12
	s_lshl_b64 s[12:13], s[8:9], 11
	s_waitcnt vmcnt(7)
	v_mov_b64_e32 v[34:35], v[22:23]
	s_waitcnt vmcnt(6)
	v_mov_b64_e32 v[38:39], v[30:31]
	s_waitcnt vmcnt(5)
	v_mov_b64_e32 v[42:43], v[18:19]
	v_mov_b64_e32 v[32:33], v[20:21]
	v_mov_b64_e32 v[36:37], v[28:29]
	v_mov_b64_e32 v[40:41], v[16:17]
	s_waitcnt vmcnt(4)
	v_mov_b64_e32 v[58:59], v[70:71]
	s_waitcnt vmcnt(0)
	v_mov_b64_e32 v[46:47], v[26:27]
	v_mov_b64_e32 v[62:63], v[68:69]
	v_mov_b64_e32 v[64:65], v[60:61]
	v_mov_b64_e32 v[66:67], v[56:57]
	v_mov_b64_e32 v[44:45], v[24:25]
	s_branch .LBB0_373

; __device__ void phase_rowprep(const float* xsrc, const bf16_t* __restrict__ m, const float* __restrict__ gpost, float* xdst, const float* __restrict__ gpre, bf16_t* __restrict__ hdst) {
;     ...
;         const int nrow = row + stride;
;         if (nrow < S) {
; #pragma unroll
;             for (int i = 0; i < 4; ++i) { xn[i] = *(const f32x4*)(xsrc + (size_t)nrow * D + i * 256 + lane * 4); mn[i] = m ? *(const bf16x4*)(m + (size_t)nrow * D + i * 256 + lane * 4) : (bf16x4){0, 0, 0, 0}; }
;         }
.LBB0_373:
	v_add_u32_e32 v48, s8, v48
	v_cmp_gt_i32_e32 vcc, s80, v48
	v_cmp_lt_i32_e64 s[0:1], s82, v48
	s_and_saveexec_b64 s[14:15], vcc
	s_cbranch_execz .LBB0_375
	v_lshl_add_u64 v[44:45], v[52:53], 0, v[176:177]
	global_load_dwordx4 v[32:35], v[44:45], off nt
	global_load_dwordx4 v[36:39], v[44:45], off offset:1024 nt
	global_load_dwordx4 v[40:43], v[44:45], off offset:2048 nt
	s_nop 0
	global_load_dwordx4 v[44:47], v[44:45], off offset:3072 nt
	s_nop 0
	global_load_dwordx2 v[58:59], v[54:55], off nt
	global_load_dwordx2 v[62:63], v[54:55], off offset:512 nt
	global_load_dwordx2 v[64:65], v[54:55], off offset:1024 nt
	global_load_dwordx2 v[66:67], v[54:55], off offset:1536 nt

; __device__ __forceinline__ int otid() { int t = threadIdx.x; asm volatile("" : "+v"(t)); return t; }
; __device__ __forceinline__ int obid() { int t = blockIdx.x; asm volatile("" : "+s"(t)); return t; }
; __device__ void phase_rowprep(const float* xsrc, const bf16_t* __restrict__ m, const float* __restrict__ gpost, float* xdst, const float* __restrict__ gpre, bf16_t* __restrict__ hdst) {
;     const int tid = otid(); const int lane = tid & 63, wave = tid >> 6;
;     const int stride = gridDim.x * 8;
;     f32x4 gp[4], gq[4];
; #pragma unroll
;     for (int i = 0; i < 4; ++i) { gp[i] = m ? *(const f32x4*)(gpost + i * 256 + lane * 4) : (f32x4){0.f, 0.f, 0.f, 0.f}; gq[i] = hdst ? *(const f32x4*)(gpre + i * 256 + lane * 4) : (f32x4){0.f, 0.f, 0.f, 0.f}; }
;     int row = obid() * 8 + wave;
;     f32x4 xn[4]; bf16x4 mn[4];
;     if (row < S) {
; #pragma unroll
;         for (int i = 0; i < 4; ++i) { xn[i] = *(const f32x4*)(xsrc + (size_t)row * D + i * 256 + lane * 4); mn[i] = m ? *(const bf16x4*)(m + (size_t)row * D + i * 256 + lane * 4) : (bf16x4){0, 0, 0, 0}; }
;     }
;     while (row < S) {
;         f32x4 xv[4]; bf16x4 mb[4];
; #pragma unroll
;         for (int i = 0; i < 4; ++i) { xv[i] = xn[i]; mb[i] = mn[i]; }
;         const int nrow = row + stride;
;         if (nrow < S) {
; #pragma unroll
;             for (int i = 0; i < 4; ++i) { xn[i] = *(const f32x4*)(xsrc + (size_t)nrow * D + i * 256 + lane * 4); mn[i] = m ? *(const bf16x4*)(m + (size_t)nrow * D + i * 256 + lane * 4) : (bf16x4){0, 0, 0, 0}; }
;         }
.LBB0_544:
	s_or_b64 exec, exec, s[4:5]
	s_add_i32 s0, s85, 8
	s_cmp_gt_u32 s0, 16
	s_mov_b64 s[0:1], -1
	s_cbranch_scc0 .LBB0_553
	v_mov_b32_e32 v32, v245
	s_mov_b32 s0, s2
	v_ashrrev_i32_e32 v0, 6, v32
	s_nop 0
	v_lshl_add_u32 v64, s0, 3, v0
	v_cmp_gt_i32_e32 vcc, s80, v64
	s_and_saveexec_b64 s[4:5], vcc
	s_cbranch_execz .LBB0_552
	v_readlane_b32 s0, v255, 16
	v_readlane_b32 s1, v255, 17
	s_ashr_i32 s1, s0, 31
	v_readlane_b32 s8, v253, 0
	s_lshl_b64 s[0:1], s[0:1], 12
	v_readlane_b32 s10, v253, 2
	v_readlane_b32 s11, v253, 3
	s_add_u32 s6, s10, s0
	v_readlane_b32 s64, v254, 27
	v_lshlrev_b32_e32 v0, 2, v32
	s_addc_u32 s7, s11, s1
	v_readlane_b32 s66, v254, 29
	v_and_b32_e32 v33, 0xfc, v0
	v_readlane_b32 s67, v254, 30
	s_add_u32 s0, s66, s0
	v_lshlrev_b32_e32 v176, 2, v33
	s_addc_u32 s1, s67, s1
	global_load_dwordx4 v[0:3], v176, s[6:7] offset:-4096
	global_load_dwordx4 v[4:7], v176, s[6:7] offset:-3072
	global_load_dwordx4 v[8:11], v176, s[0:1]
	global_load_dwordx4 v[12:15], v176, s[0:1] offset:1024
	global_load_dwordx4 v[16:19], v176, s[6:7] offset:-2048
	global_load_dwordx4 v[20:23], v176, s[6:7] offset:-1024
	global_load_dwordx4 v[24:27], v176, s[0:1] offset:2048
	global_load_dwordx4 v[28:31], v176, s[0:1] offset:3072
	v_ashrrev_i32_e32 v65, 31, v64
	v_lshlrev_b64 v[34:35], 12, v[64:65]
	v_readlane_b32 s0, v253, 18
	v_lshl_add_u64 v[66:67], s[58:59], 0, v[34:35]
	v_lshlrev_b64 v[36:37], 11, v[64:65]
	v_readlane_b32 s1, v253, 19
	v_lshl_add_u64 v[34:35], v[66:67], 0, v[176:177]
	v_lshlrev_b32_e32 v176, 1, v33
	v_lshl_add_u64 v[38:39], s[0:1], 0, v[36:37]
	v_lshl_add_u64 v[38:39], v[38:39], 0, v[176:177]
	global_load_dwordx4 v[60:63], v[34:35], off nt
	global_load_dwordx4 v[56:59], v[34:35], off offset:1024 nt
	global_load_dwordx4 v[52:55], v[34:35], off offset:2048 nt
	global_load_dwordx2 v[90:91], v[38:39], off nt
	global_load_dwordx2 v[88:89], v[38:39], off offset:512 nt
	global_load_dwordx2 v[86:87], v[38:39], off offset:1024 nt
	global_load_dwordx2 v[84:85], v[38:39], off offset:1536 nt
	global_load_dwordx4 v[48:51], v[34:35], off offset:3072 nt
	v_and_b32_e32 v33, 64, v228
	v_xor_b32_e32 v34, 32, v228
	v_and_b32_e32 v42, 63, v32
	v_add_u32_e32 v32, 64, v33
	v_xor_b32_e32 v35, 16, v228
	v_cmp_lt_i32_e32 vcc, v34, v32
	v_xor_b32_e32 v38, 8, v228
	v_xor_b32_e32 v39, 4, v228
	v_cndmask_b32_e32 v33, v228, v34, vcc
	v_cmp_lt_i32_e32 vcc, v35, v32
	v_xor_b32_e32 v40, 2, v228
	v_xor_b32_e32 v41, 1, v228
	v_cndmask_b32_e32 v34, v228, v35, vcc
	v_cmp_lt_i32_e32 vcc, v38, v32
	s_waitcnt lgkmcnt(0)
	s_lshl_b32 s8, s26, 3
	v_lshlrev_b32_e32 v65, 2, v33
	v_cndmask_b32_e32 v35, v228, v38, vcc
	v_cmp_lt_i32_e32 vcc, v39, v32
	v_readlane_b32 s9, v253, 1
	v_lshlrev_b32_e32 v92, 2, v34
	v_cndmask_b32_e32 v38, v228, v39, vcc
	v_cmp_lt_i32_e32 vcc, v40, v32
	v_lshlrev_b32_e32 v93, 2, v35
	v_readlane_b32 s12, v253, 4
	v_cndmask_b32_e32 v39, v228, v40, vcc
	v_cmp_lt_i32_e32 vcc, v41, v32
	v_readlane_b32 s13, v253, 5
	v_lshlrev_b32_e32 v68, 4, v42
	v_cndmask_b32_e32 v32, v228, v41, vcc
	v_lshlrev_b32_e32 v96, 2, v32
	v_add_u32_e32 v32, s8, v64
	v_ashrrev_i32_e32 v33, 31, v32
	v_lshlrev_b64 v[34:35], 12, v[32:33]
	v_lshlrev_b64 v[32:33], 11, v[32:33]
	v_lshl_add_u64 v[70:71], s[60:61], 0, v[36:37]
	v_lshlrev_b32_e32 v94, 2, v38
	v_lshlrev_b32_e32 v95, 2, v39
	s_ashr_i32 s9, s8, 31
	v_lshlrev_b32_e32 v176, 3, v42
	v_lshl_add_u64 v[72:73], s[58:59], 0, v[34:35]
	v_lshl_add_u64 v[74:75], s[60:61], 0, v[32:33]
	v_mov_b32_e32 v69, v177
	s_mov_b64 s[6:7], 0
	s_lshl_b64 s[10:11], s[8:9], 11
	s_lshl_b64 s[12:13], s[8:9], 12
	v_readlane_b32 s14, v253, 6
	v_readlane_b32 s15, v253, 7
	v_readlane_b32 s65, v254, 28
	v_readlane_b32 s68, v254, 31
	v_readlane_b32 s69, v254, 32
	v_readlane_b32 s70, v254, 33
	v_readlane_b32 s71, v254, 34
	v_readlane_b32 s72, v254, 35
	v_readlane_b32 s73, v254, 36
	v_readlane_b32 s74, v254, 37
	v_readlane_b32 s75, v254, 38
	v_readlane_b32 s76, v254, 39
	v_readlane_b32 s77, v254, 40
	v_readlane_b32 s78, v254, 41
	v_readlane_b32 s79, v254, 42
	s_waitcnt vmcnt(7)
	v_mov_b64_e32 v[32:33], v[60:61]
	s_waitcnt vmcnt(6)
	v_mov_b64_e32 v[36:37], v[56:57]
	s_waitcnt vmcnt(5)
	v_mov_b64_e32 v[40:41], v[52:53]
	v_mov_b64_e32 v[34:35], v[62:63]
	v_mov_b64_e32 v[38:39], v[58:59]
	v_mov_b64_e32 v[42:43], v[54:55]
	s_waitcnt vmcnt(4)
	v_mov_b64_e32 v[76:77], v[90:91]
	s_waitcnt vmcnt(0)
	v_mov_b64_e32 v[44:45], v[48:49]
	v_mov_b64_e32 v[78:79], v[88:89]
	v_mov_b64_e32 v[80:81], v[86:87]
	v_mov_b64_e32 v[82:83], v[84:85]
	v_mov_b64_e32 v[46:47], v[50:51]
	s_branch .LBB0_548

; __device__ void phase_rowprep(const float* xsrc, const bf16_t* __restrict__ m, const float* __restrict__ gpost, float* xdst, const float* __restrict__ gpre, bf16_t* __restrict__ hdst) {
;     ...
;         const int nrow = row + stride;
;         if (nrow < S) {
; #pragma unroll
;             for (int i = 0; i < 4; ++i) { xn[i] = *(const f32x4*)(xsrc + (size_t)nrow * D + i * 256 + lane * 4); mn[i] = m ? *(const bf16x4*)(m + (size_t)nrow * D + i * 256 + lane * 4) : (bf16x4){0, 0, 0, 0}; }
;         }
.LBB0_548:
	v_add_u32_e32 v64, s8, v64
	v_cmp_gt_i32_e32 vcc, s80, v64
	v_cmp_lt_i32_e64 s[0:1], s82, v64
	s_and_saveexec_b64 s[14:15], vcc
	s_cbranch_execz .LBB0_550
	v_lshl_add_u64 v[32:33], v[74:75], 0, v[176:177]
	v_add_co_u32_e32 v82, vcc, 0x9058000, v32
	v_lshl_add_u64 v[44:45], v[72:73], 0, v[68:69]
	s_nop 0
	v_addc_co_u32_e32 v83, vcc, 0, v33, vcc
	global_load_dwordx4 v[32:35], v[44:45], off nt
	global_load_dwordx4 v[36:39], v[44:45], off offset:1024 nt
	global_load_dwordx4 v[40:43], v[44:45], off offset:2048 nt
	s_nop 0
	global_load_dwordx4 v[44:47], v[44:45], off offset:3072 nt
	s_nop 0
	global_load_dwordx2 v[76:77], v[82:83], off nt
	global_load_dwordx2 v[78:79], v[82:83], off offset:512 nt
	global_load_dwordx2 v[80:81], v[82:83], off offset:1024 nt
	s_nop 0
	global_load_dwordx2 v[82:83], v[82:83], off offset:1536 nt
